# A-loop DMA: inst offset:2048 pairs (4 M0 writes instead of 8, 16 fewer SALU per step)
# baseline (speedup 1.0000x reference)
; DI void attn_item_A(const Params& p, int layer, int b, int head, int qb, u16* sm, float lam, float lam_init, int wv) {
;     ...
;   auto dma_tile = [&](int T, int c) {
;     const int k0 = 64 * T;
;     u16* Kd = Kb0 + c * (2 * 64 * 64) + wp * (8 * 64);
; #pragma unroll
;     for (int i = 0; i < 4; ++i) {
;       __builtin_amdgcn_global_load_lds((const unsigned*)(kg + (size_t)(k0 + row0 + 16 * i) * DIN), (unsigned*)(Kd + i * 16 * 64), 16, 0, 0);
;       __builtin_amdgcn_global_load_lds((const unsigned*)(vg + (size_t)(row0 + 16 * i) * SEQ + k0), (unsigned*)(Kd + 64 * 64 + i * 16 * 64), 16, 0, 0);
;     }
;   };
;   if (v0) dma_tile(T0, 0);
;   asm volatile("" :: "v"(qf[0]), "v"(qf[1]), "v"(qf[2]), "v"(qf[3]));
;   asm volatile("s_waitcnt vmcnt(0)" ::: "memory");
;   __syncthreads();
;   for (int j = 0; j < npairs; ++j) {
;     if (j + 1 < npairs) dma_tile(T0 - 2 * (j + 1), (j + 1) & 1);
;     if (j > 0 || v0) {
;       const int T = T0 - 2 * j;
;       const u16* Ks = Kb0 + (j & 1) * (2 * 64 * 64);
;       const u16* Vs = Ks + 64 * 64;
;       const int k0 = 64 * T;
;       const bool need_mask = (T == qb);
;       const int dl = qpos - k0 - 4 * h;
;       diff_softmax_pv(qf, Ks, Vs, m0, ls0, ls1, ones, o, sl2, dl, need_mask, !started, r, h, 64, lo);
.LBB0_276:
	s_or_b64 exec, exec, s[18:19]
	s_waitcnt vmcnt(0)
	v_and_b32_e32 v205, 60, v125
	s_waitcnt vmcnt(0) lgkmcnt(0)
	s_barrier
	s_and_saveexec_b64 s[18:19], vcc
	s_cbranch_execz .LBB0_292
	v_add_u32_e32 v66, v120, v171
	v_sub_u32_e32 v66, v66, v124
	v_lshlrev_b32_e32 v67, 6, v118
	v_sub_u32_e32 v66, v66, v67
	v_lshlrev_b32_e32 v206, 6, v173
	v_lshlrev_b32_e32 v67, 6, v119
	v_sub_u32_e32 v66, v66, v206
	v_and_b32_e32 v67, 0xffffff80, v67
	v_sub_u32_e32 v66, v66, v67
	v_add_u32_e32 v207, 0x2040, v66
	v_add_u32_e32 v66, v118, v173
	s_movk_i32 s2, 0xff7f
	v_add3_u32 v208, v66, v123, s2
	v_or_b32_e32 v66, v121, v67
	v_cmp_gt_u32_e64 s[36:37], 16, v171
	v_add_u32_e32 v209, v66, v122
	v_add_u32_e32 v210, 0xffffff00, v67
	v_add_u32_e32 v72, v206, v209
	v_add_u32_e32 v68, 0xffffff00, v72
	v_mad_i64_i32 v[68:69], s[38:39], v68, s8, v[160:161]
	v_readlane_b32 s22, v250, 19
	v_add_u32_e32 v66, v206, v210
	v_ashrrev_i32_e32 v67, 31, v66
	v_lshl_add_u64 v[68:69], v[68:69], 0, s[68:69]
	v_lshlrev_b64 v[66:67], 1, v[66:67]
	v_or_b32_e32 v74, v121, v122
	v_subrev_u32_e32 v75, s22, v160
	v_lshl_add_u64 v[70:71], v[162:163], 0, v[66:67]
	v_mul_u32_u24_e32 v76, 0x1a00, v74
	v_lshlrev_b32_e32 v77, 14, v74
	v_add_u32_e32 v76, v76, v75
	v_add_u32_e32 v77, v77, v75
	v_sub_co_u32_e32 v68, vcc, v68, v76
	s_nop 1
	v_subbrev_co_u32_e32 v69, vcc, 0, v69, vcc
	v_sub_co_u32_e32 v70, vcc, v70, v77
	s_nop 1
	v_subbrev_co_u32_e32 v71, vcc, 0, v71, vcc
	v_mov_b32_e32 v160, v76
	v_readfirstlane_b32 s98, v68
	v_readfirstlane_b32 s99, v69
	v_readfirstlane_b32 s100, v70
	v_readfirstlane_b32 s101, v71
	v_readfirstlane_b32 s87, v177
	v_add_u32_e32 v161, 0x19800, v76
	v_add_u32_e32 v162, 0x34000, v76
	v_add_u32_e32 v163, 0x4d800, v76
	v_mov_b32_e32 v164, v77
	v_add_u32_e32 v165, 0x3f800, v77
	v_add_u32_e32 v166, 0x80000, v77
	v_add_u32_e32 v167, 0xbf800, v77
	s_movk_i32 s64, 0x2000
	s_mov_b32 s65, 0
	s_mov_b64 s[40:41], 0
	s_mov_b64 s[42:43], s[4:5]
	s_branch .LBB0_279

; DI void attn_item_A(const Params& p, int layer, int b, int head, int qb, u16* sm, float lam, float lam_init, int wv) {
;     ...
;   auto dma_tile = [&](int T, int c) {
;     const int k0 = 64 * T;
;     u16* Kd = Kb0 + c * (2 * 64 * 64) + wp * (8 * 64);
; #pragma unroll
;     for (int i = 0; i < 4; ++i) {
;       __builtin_amdgcn_global_load_lds((const unsigned*)(kg + (size_t)(k0 + row0 + 16 * i) * DIN), (unsigned*)(Kd + i * 16 * 64), 16, 0, 0);
;       __builtin_amdgcn_global_load_lds((const unsigned*)(vg + (size_t)(row0 + 16 * i) * SEQ + k0), (unsigned*)(Kd + 64 * 64 + i * 16 * 64), 16, 0, 0);
;     }
;   };
;     ...
;   for (int j = 0; j < npairs; ++j) {
;     if (j + 1 < npairs) dma_tile(T0 - 2 * (j + 1), (j + 1) & 1);
.LBB0_279:
	s_add_i32 s65, s65, 1
	v_cmp_lt_i32_e32 vcc, s65, v180
	s_and_saveexec_b64 s[2:3], vcc
	s_cbranch_execz .LBB0_281
	s_add_i32 s38, s64, 0x2000
	s_and_b32 s38, s38, 0x2000
	s_lshl_b32 s38, s38, 1
	s_add_i32 s38, s38, s87
	s_mov_b32 m0, s38
	s_add_i32 s22, s38, 0x2000
	global_load_lds_dwordx4 v160, s[98:99]
	global_load_lds_dwordx4 v161, s[98:99] offset:2048
	s_mov_b32 m0, s22
	s_add_i32 s32, s38, 0x1000
	global_load_lds_dwordx4 v164, s[100:101]
	global_load_lds_dwordx4 v165, s[100:101] offset:2048
	s_mov_b32 m0, s32
	s_add_i32 s22, s38, 0x3000
	global_load_lds_dwordx4 v162, s[98:99]
	global_load_lds_dwordx4 v163, s[98:99] offset:2048
	s_mov_b32 m0, s22
	s_add_u32 s98, s98, 0xfff30000
	s_addc_u32 s99, s99, -1
	global_load_lds_dwordx4 v166, s[100:101]
	global_load_lds_dwordx4 v167, s[100:101] offset:2048
	s_sub_u32 s100, s100, 0x100
	s_subb_u32 s101, s101, 0
